# P1/P8: wave halves stay staggered across unit boundaries (alignment barrier only for the last unit, restore barrier removed), stacked on v66
# baseline (speedup 1.0000x reference)
.LBB0_201:
	ds_read_b128 v[152:155], v145
	ds_read_b128 v[156:159], v145 offset:1024
	ds_read_b128 v[160:163], v145 offset:2048
	ds_read_b128 v[164:167], v145 offset:3072
	ds_read_b128 v[168:171], v146
	ds_read_b128 v[172:175], v146 offset:1024
	ds_read_b128 v[176:179], v146 offset:2048
	ds_read_b128 v[180:183], v146 offset:3072
	s_add_u32 s12, s24, s6
	s_addc_u32 s13, s25, s7
	s_add_u32 s12, s12, 0x200
	s_addc_u32 s13, s13, 0
	s_add_u32 s14, s46, s6
	s_addc_u32 s15, s47, s7
	s_cmpk_eq_i32 s6, 0x600
	s_cselect_b32 s81, s48, s13
	s_cselect_b32 s80, s49, s12
	s_cselect_b32 s13, s89, s15
	s_cselect_b32 s12, s91, s14
	v_lshl_add_u64 v[184:185], v[140:141], 0, s[6:7]
	s_mov_b32 m0, vcc_lo
	v_lshl_add_u64 v[220:221], v[184:185], 0, s[84:85]
	ds_read_b128 v[188:191], v147
	ds_read_b128 v[192:195], v147 offset:1024
	ds_read_b128 v[196:199], v147 offset:2048
	ds_read_b128 v[200:203], v147 offset:3072
	ds_read_b128 v[204:207], v147 offset:4096
	ds_read_b128 v[208:211], v147 offset:5120
	ds_read_b128 v[212:215], v147 offset:6144
	ds_read_b128 v[216:219], v147 offset:7168
	global_load_lds_dwordx4 v[220:221], off
	v_lshl_add_u64 v[184:185], v[184:185], 0, s[86:87]
	s_mov_b32 m0, vcc_hi
	s_nop 0
	global_load_lds_dwordx4 v[184:185], off
	s_waitcnt vmcnt(8)
	s_waitcnt lgkmcnt(0)
	s_waitcnt lgkmcnt(0)
	v_mfma_f32_16x16x32_bf16 v[118:121], v[152:155], v[188:191], v[118:121]
	v_mfma_f32_16x16x32_bf16 v[114:117], v[160:163], v[188:191], v[114:117]
	s_barrier
	s_setprio 1
	v_mfma_f32_16x16x32_bf16 v[102:105], v[152:155], v[196:199], v[102:105]
	v_mfma_f32_16x16x32_bf16 v[98:101], v[160:163], v[196:199], v[98:101]
	v_mfma_f32_16x16x32_bf16 v[86:89], v[152:155], v[204:207], v[86:89]
	v_mfma_f32_16x16x32_bf16 v[82:85], v[160:163], v[204:207], v[82:85]
	v_mfma_f32_16x16x32_bf16 v[70:73], v[152:155], v[212:215], v[70:73]
	v_mfma_f32_16x16x32_bf16 v[62:65], v[160:163], v[212:215], v[62:65]
	v_mfma_f32_16x16x32_bf16 v[118:121], v[156:159], v[192:195], v[118:121]
	v_mfma_f32_16x16x32_bf16 v[114:117], v[164:167], v[192:195], v[114:117]
	v_mfma_f32_16x16x32_bf16 v[102:105], v[156:159], v[200:203], v[102:105]
	v_mfma_f32_16x16x32_bf16 v[98:101], v[164:167], v[200:203], v[98:101]
	v_mfma_f32_16x16x32_bf16 v[86:89], v[156:159], v[208:211], v[86:89]
	v_mfma_f32_16x16x32_bf16 v[82:85], v[164:167], v[208:211], v[82:85]
	v_mfma_f32_16x16x32_bf16 v[70:73], v[156:159], v[216:219], v[70:73]
	v_mfma_f32_16x16x32_bf16 v[62:65], v[164:167], v[216:219], v[62:65]
	s_setprio 0
	s_setprio 1
	v_mfma_f32_16x16x32_bf16 v[126:129], v[168:171], v[188:191], v[126:129]
	v_mfma_f32_16x16x32_bf16 v[122:125], v[176:179], v[188:191], v[122:125]
	v_mfma_f32_16x16x32_bf16 v[110:113], v[168:171], v[196:199], v[110:113]
	v_mfma_f32_16x16x32_bf16 v[106:109], v[176:179], v[196:199], v[106:109]
	v_mfma_f32_16x16x32_bf16 v[94:97], v[168:171], v[204:207], v[94:97]
	v_mfma_f32_16x16x32_bf16 v[90:93], v[176:179], v[204:207], v[90:93]
	v_mfma_f32_16x16x32_bf16 v[78:81], v[168:171], v[212:215], v[78:81]
	v_mfma_f32_16x16x32_bf16 v[74:77], v[176:179], v[212:215], v[74:77]
	v_mfma_f32_16x16x32_bf16 v[126:129], v[172:175], v[192:195], v[126:129]
	v_mfma_f32_16x16x32_bf16 v[122:125], v[180:183], v[192:195], v[122:125]
	v_mfma_f32_16x16x32_bf16 v[110:113], v[172:175], v[200:203], v[110:113]
	v_mfma_f32_16x16x32_bf16 v[106:109], v[180:183], v[200:203], v[106:109]
	v_mfma_f32_16x16x32_bf16 v[94:97], v[172:175], v[208:211], v[94:97]
	v_mfma_f32_16x16x32_bf16 v[90:93], v[180:183], v[208:211], v[90:93]
	v_mfma_f32_16x16x32_bf16 v[78:81], v[172:175], v[216:219], v[78:81]
	v_mfma_f32_16x16x32_bf16 v[74:77], v[180:183], v[216:219], v[74:77]
	s_setprio 0
	s_barrier
	s_mov_b32 m0, s8
	v_lshl_add_u64 v[184:185], s[12:13], 0, v[132:133]
	ds_read_b128 v[188:191], v147 offset:16384
	ds_read_b128 v[192:195], v147 offset:17408
	ds_read_b128 v[196:199], v147 offset:18432
	ds_read_b128 v[200:203], v147 offset:19456
	ds_read_b128 v[204:207], v147 offset:20480
	ds_read_b128 v[208:211], v147 offset:21504
	ds_read_b128 v[212:215], v147 offset:22528
	ds_read_b128 v[216:219], v147 offset:23552
	global_load_lds_dwordx4 v[184:185], off
	v_lshl_add_u64 v[220:221], v[184:185], 0, s[26:27]
	s_mov_b32 m0, s9
	s_nop 0
	global_load_lds_dwordx4 v[220:221], off
	v_lshl_add_u64 v[220:221], v[184:185], 0, s[28:29]
	s_mov_b32 m0, s33
	s_nop 0
	global_load_lds_dwordx4 v[220:221], off
	v_lshl_add_u64 v[220:221], v[184:185], 0, s[30:31]
	s_mov_b32 m0, s2
	s_nop 0
	global_load_lds_dwordx4 v[220:221], off
	v_lshl_add_u64 v[220:221], s[80:81], 0, v[130:131]
	s_mov_b32 m0, s11
	v_lshl_add_u64 v[222:223], v[220:221], 0, s[26:27]
	global_load_lds_dwordx4 v[220:221], off
	s_mov_b32 m0, s54
	s_nop 0
	global_load_lds_dwordx4 v[222:223], off
	s_waitcnt vmcnt(8)
	s_waitcnt lgkmcnt(0)
	s_waitcnt lgkmcnt(0)
	v_mfma_f32_16x16x32_bf16 v[54:57], v[152:155], v[188:191], v[54:57]
	v_mfma_f32_16x16x32_bf16 v[50:53], v[160:163], v[188:191], v[50:53]
	s_barrier
	s_setprio 1
	v_mfma_f32_16x16x32_bf16 v[38:41], v[152:155], v[196:199], v[38:41]
	v_mfma_f32_16x16x32_bf16 v[34:37], v[160:163], v[196:199], v[34:37]
	v_mfma_f32_16x16x32_bf16 v[22:25], v[152:155], v[204:207], v[22:25]
	v_mfma_f32_16x16x32_bf16 v[18:21], v[160:163], v[204:207], v[18:21]
	v_mfma_f32_16x16x32_bf16 v[6:9], v[152:155], v[212:215], v[6:9]
	v_mfma_f32_16x16x32_bf16 v[2:5], v[160:163], v[212:215], v[2:5]
	v_mfma_f32_16x16x32_bf16 v[54:57], v[156:159], v[192:195], v[54:57]
	v_mfma_f32_16x16x32_bf16 v[50:53], v[164:167], v[192:195], v[50:53]
	v_mfma_f32_16x16x32_bf16 v[38:41], v[156:159], v[200:203], v[38:41]
	v_mfma_f32_16x16x32_bf16 v[34:37], v[164:167], v[200:203], v[34:37]
	v_mfma_f32_16x16x32_bf16 v[22:25], v[156:159], v[208:211], v[22:25]
	v_mfma_f32_16x16x32_bf16 v[18:21], v[164:167], v[208:211], v[18:21]
	v_mfma_f32_16x16x32_bf16 v[6:9], v[156:159], v[216:219], v[6:9]
	v_mfma_f32_16x16x32_bf16 v[2:5], v[164:167], v[216:219], v[2:5]
	s_setprio 0
	s_setprio 1
	v_mfma_f32_16x16x32_bf16 v[66:69], v[168:171], v[188:191], v[66:69]
	v_mfma_f32_16x16x32_bf16 v[58:61], v[176:179], v[188:191], v[58:61]
	v_mfma_f32_16x16x32_bf16 v[46:49], v[168:171], v[196:199], v[46:49]
	v_mfma_f32_16x16x32_bf16 v[42:45], v[176:179], v[196:199], v[42:45]
	v_mfma_f32_16x16x32_bf16 v[30:33], v[168:171], v[204:207], v[30:33]
	v_mfma_f32_16x16x32_bf16 v[26:29], v[176:179], v[204:207], v[26:29]
	v_mfma_f32_16x16x32_bf16 v[14:17], v[168:171], v[212:215], v[14:17]
	v_mfma_f32_16x16x32_bf16 v[10:13], v[176:179], v[212:215], v[10:13]
	v_mfma_f32_16x16x32_bf16 v[66:69], v[172:175], v[192:195], v[66:69]
	v_mfma_f32_16x16x32_bf16 v[58:61], v[180:183], v[192:195], v[58:61]
	v_mfma_f32_16x16x32_bf16 v[46:49], v[172:175], v[200:203], v[46:49]
	v_mfma_f32_16x16x32_bf16 v[42:45], v[180:183], v[200:203], v[42:45]
	v_mfma_f32_16x16x32_bf16 v[30:33], v[172:175], v[208:211], v[30:33]
	v_mfma_f32_16x16x32_bf16 v[26:29], v[180:183], v[208:211], v[26:29]
	v_mfma_f32_16x16x32_bf16 v[14:17], v[172:175], v[216:219], v[14:17]
	v_mfma_f32_16x16x32_bf16 v[10:13], v[180:183], v[216:219], v[10:13]
	s_setprio 0
	s_barrier
	ds_read_b128 v[152:155], v149
	ds_read_b128 v[156:159], v149 offset:1024
	ds_read_b128 v[160:163], v149 offset:2048
	ds_read_b128 v[164:167], v149 offset:3072
	ds_read_b128 v[168:171], v150
	ds_read_b128 v[172:175], v150 offset:1024
	ds_read_b128 v[176:179], v150 offset:2048
	ds_read_b128 v[180:183], v150 offset:3072
	s_mov_b32 m0, s55
	v_lshl_add_u64 v[222:223], v[220:221], 0, s[28:29]
	ds_read_b128 v[188:191], v147 offset:32768
	ds_read_b128 v[192:195], v147 offset:33792
	ds_read_b128 v[196:199], v147 offset:34816
	ds_read_b128 v[200:203], v147 offset:35840
	ds_read_b128 v[204:207], v147 offset:36864
	ds_read_b128 v[208:211], v147 offset:37888
	ds_read_b128 v[212:215], v147 offset:38912
	ds_read_b128 v[216:219], v147 offset:39936
	global_load_lds_dwordx4 v[222:223], off
	v_lshl_add_u64 v[222:223], v[220:221], 0, s[30:31]
	s_mov_b32 m0, s56
	s_nop 0
	global_load_lds_dwordx4 v[222:223], off
	s_waitcnt vmcnt(8)
	s_waitcnt lgkmcnt(0)
	s_waitcnt lgkmcnt(0)
	v_mfma_f32_16x16x32_bf16 v[118:121], v[152:155], v[188:191], v[118:121]
	v_mfma_f32_16x16x32_bf16 v[114:117], v[160:163], v[188:191], v[114:117]
	s_barrier
	s_setprio 1
	v_mfma_f32_16x16x32_bf16 v[102:105], v[152:155], v[196:199], v[102:105]
	v_mfma_f32_16x16x32_bf16 v[98:101], v[160:163], v[196:199], v[98:101]
	v_mfma_f32_16x16x32_bf16 v[86:89], v[152:155], v[204:207], v[86:89]
	v_mfma_f32_16x16x32_bf16 v[82:85], v[160:163], v[204:207], v[82:85]
	v_mfma_f32_16x16x32_bf16 v[70:73], v[152:155], v[212:215], v[70:73]
	v_mfma_f32_16x16x32_bf16 v[62:65], v[160:163], v[212:215], v[62:65]
	v_mfma_f32_16x16x32_bf16 v[118:121], v[156:159], v[192:195], v[118:121]
	v_mfma_f32_16x16x32_bf16 v[114:117], v[164:167], v[192:195], v[114:117]
	v_mfma_f32_16x16x32_bf16 v[102:105], v[156:159], v[200:203], v[102:105]
	v_mfma_f32_16x16x32_bf16 v[98:101], v[164:167], v[200:203], v[98:101]
	v_mfma_f32_16x16x32_bf16 v[86:89], v[156:159], v[208:211], v[86:89]
	v_mfma_f32_16x16x32_bf16 v[82:85], v[164:167], v[208:211], v[82:85]
	v_mfma_f32_16x16x32_bf16 v[70:73], v[156:159], v[216:219], v[70:73]
	v_mfma_f32_16x16x32_bf16 v[62:65], v[164:167], v[216:219], v[62:65]
	s_setprio 0
	s_setprio 1
	v_mfma_f32_16x16x32_bf16 v[126:129], v[168:171], v[188:191], v[126:129]
	v_mfma_f32_16x16x32_bf16 v[122:125], v[176:179], v[188:191], v[122:125]
	v_mfma_f32_16x16x32_bf16 v[110:113], v[168:171], v[196:199], v[110:113]
	v_mfma_f32_16x16x32_bf16 v[106:109], v[176:179], v[196:199], v[106:109]
	v_mfma_f32_16x16x32_bf16 v[94:97], v[168:171], v[204:207], v[94:97]
	v_mfma_f32_16x16x32_bf16 v[90:93], v[176:179], v[204:207], v[90:93]
	v_mfma_f32_16x16x32_bf16 v[78:81], v[168:171], v[212:215], v[78:81]
	v_mfma_f32_16x16x32_bf16 v[74:77], v[176:179], v[212:215], v[74:77]
	v_mfma_f32_16x16x32_bf16 v[126:129], v[172:175], v[192:195], v[126:129]
	v_mfma_f32_16x16x32_bf16 v[122:125], v[180:183], v[192:195], v[122:125]
	v_mfma_f32_16x16x32_bf16 v[110:113], v[172:175], v[200:203], v[110:113]
	v_mfma_f32_16x16x32_bf16 v[106:109], v[180:183], v[200:203], v[106:109]
	v_mfma_f32_16x16x32_bf16 v[94:97], v[172:175], v[208:211], v[94:97]
	v_mfma_f32_16x16x32_bf16 v[90:93], v[180:183], v[208:211], v[90:93]
	v_mfma_f32_16x16x32_bf16 v[78:81], v[172:175], v[216:219], v[78:81]
	v_mfma_f32_16x16x32_bf16 v[74:77], v[180:183], v[216:219], v[74:77]
	s_setprio 0
	s_barrier
	s_mov_b32 m0, s3
	v_lshl_add_u64 v[222:223], v[184:185], 0, s[38:39]
	ds_read_b128 v[188:191], v147 offset:49152
	ds_read_b128 v[192:195], v147 offset:50176
	ds_read_b128 v[196:199], v147 offset:51200
	ds_read_b128 v[200:203], v147 offset:52224
	ds_read_b128 v[204:207], v147 offset:53248
	ds_read_b128 v[208:211], v147 offset:54272
	ds_read_b128 v[212:215], v147 offset:55296
	ds_read_b128 v[216:219], v147 offset:56320
	global_load_lds_dwordx4 v[222:223], off
	v_lshl_add_u64 v[222:223], v[184:185], 0, s[40:41]
	s_mov_b32 m0, s34
	s_nop 0
	global_load_lds_dwordx4 v[222:223], off
	v_lshl_add_u64 v[222:223], v[184:185], 0, s[42:43]
	s_mov_b32 m0, s35
	v_lshl_add_u64 v[184:185], v[184:185], 0, s[44:45]
	global_load_lds_dwordx4 v[222:223], off
	s_mov_b32 m0, s36
	s_nop 0
	global_load_lds_dwordx4 v[184:185], off
	v_lshl_add_u64 v[184:185], v[220:221], 0, s[38:39]
	s_mov_b32 m0, s57
	s_nop 0
	global_load_lds_dwordx4 v[184:185], off
	v_lshl_add_u64 v[184:185], v[220:221], 0, s[40:41]
	s_mov_b32 m0, s58
	s_nop 0
	global_load_lds_dwordx4 v[184:185], off
	s_waitcnt vmcnt(8)
	s_waitcnt lgkmcnt(0)
	s_waitcnt lgkmcnt(0)
	v_mfma_f32_16x16x32_bf16 v[54:57], v[152:155], v[188:191], v[54:57]
	v_mfma_f32_16x16x32_bf16 v[50:53], v[160:163], v[188:191], v[50:53]
	s_barrier
	s_setprio 1
	v_mfma_f32_16x16x32_bf16 v[38:41], v[152:155], v[196:199], v[38:41]
	v_mfma_f32_16x16x32_bf16 v[34:37], v[160:163], v[196:199], v[34:37]
	v_mfma_f32_16x16x32_bf16 v[22:25], v[152:155], v[204:207], v[22:25]
	v_mfma_f32_16x16x32_bf16 v[18:21], v[160:163], v[204:207], v[18:21]
	v_mfma_f32_16x16x32_bf16 v[6:9], v[152:155], v[212:215], v[6:9]
	v_mfma_f32_16x16x32_bf16 v[2:5], v[160:163], v[212:215], v[2:5]
	v_mfma_f32_16x16x32_bf16 v[54:57], v[156:159], v[192:195], v[54:57]
	v_mfma_f32_16x16x32_bf16 v[50:53], v[164:167], v[192:195], v[50:53]
	v_mfma_f32_16x16x32_bf16 v[38:41], v[156:159], v[200:203], v[38:41]
	v_mfma_f32_16x16x32_bf16 v[34:37], v[164:167], v[200:203], v[34:37]
	v_mfma_f32_16x16x32_bf16 v[22:25], v[156:159], v[208:211], v[22:25]
	v_mfma_f32_16x16x32_bf16 v[18:21], v[164:167], v[208:211], v[18:21]
	v_mfma_f32_16x16x32_bf16 v[6:9], v[156:159], v[216:219], v[6:9]
	v_mfma_f32_16x16x32_bf16 v[2:5], v[164:167], v[216:219], v[2:5]
	s_setprio 0
	s_setprio 1
	v_mfma_f32_16x16x32_bf16 v[66:69], v[168:171], v[188:191], v[66:69]
	v_mfma_f32_16x16x32_bf16 v[58:61], v[176:179], v[188:191], v[58:61]
	v_mfma_f32_16x16x32_bf16 v[46:49], v[168:171], v[196:199], v[46:49]
	v_mfma_f32_16x16x32_bf16 v[42:45], v[176:179], v[196:199], v[42:45]
	v_mfma_f32_16x16x32_bf16 v[30:33], v[168:171], v[204:207], v[30:33]
	v_mfma_f32_16x16x32_bf16 v[26:29], v[176:179], v[204:207], v[26:29]
	v_mfma_f32_16x16x32_bf16 v[14:17], v[168:171], v[212:215], v[14:17]
	v_mfma_f32_16x16x32_bf16 v[10:13], v[176:179], v[212:215], v[10:13]
	v_mfma_f32_16x16x32_bf16 v[66:69], v[172:175], v[192:195], v[66:69]
	v_mfma_f32_16x16x32_bf16 v[58:61], v[180:183], v[192:195], v[58:61]
	v_mfma_f32_16x16x32_bf16 v[46:49], v[172:175], v[200:203], v[46:49]
	v_mfma_f32_16x16x32_bf16 v[42:45], v[180:183], v[200:203], v[42:45]
	v_mfma_f32_16x16x32_bf16 v[30:33], v[172:175], v[208:211], v[30:33]
	v_mfma_f32_16x16x32_bf16 v[26:29], v[180:183], v[208:211], v[26:29]
	v_mfma_f32_16x16x32_bf16 v[14:17], v[172:175], v[216:219], v[14:17]
	v_mfma_f32_16x16x32_bf16 v[10:13], v[180:183], v[216:219], v[10:13]
	s_setprio 0
	s_barrier
	s_add_i32 s37, s37, 2
	s_add_u32 s6, s6, 0x100
	s_addc_u32 s7, s7, 0
	s_cmp_gt_u32 s37, 13
	s_cbranch_scc0 .LBB0_201
	s_and_b64 vcc, exec, s[62:63]
	s_cbranch_vccz .LBB0_204
	s_cmp_eq_u64 s[4:5], 0
	s_cbranch_scc1 .LBB0_204
	s_barrier

.Lwtd_7:
	s_cbranch_vccnz .LBB0_211
	v_readlane_b32 s0, v255, 13
	v_readlane_b32 s1, v255, 14
	s_andn2_b64 vcc, exec, s[0:1]
	s_cbranch_vccnz .LBB0_194
	s_branch .LBB0_194

.LBB0_1718:
	ds_read_b128 v[152:155], v145
	ds_read_b128 v[156:159], v145 offset:1024
	ds_read_b128 v[160:163], v145 offset:2048
	ds_read_b128 v[164:167], v145 offset:3072
	ds_read_b128 v[168:171], v146
	ds_read_b128 v[172:175], v146 offset:1024
	ds_read_b128 v[176:179], v146 offset:2048
	ds_read_b128 v[180:183], v146 offset:3072
	s_add_u32 s18, s14, s6
	s_addc_u32 s19, s15, s7
	s_add_u32 s18, s18, 0x200
	s_addc_u32 s19, s19, 0
	s_add_u32 s20, s50, s6
	s_addc_u32 s21, s51, s7
	s_cmpk_eq_i32 s6, 0x600
	s_cselect_b32 s19, s73, s19
	s_cselect_b32 s18, s93, s18
	s_cselect_b32 s21, s67, s21
	s_cselect_b32 s20, s94, s20
	v_lshl_add_u64 v[184:185], v[140:141], 0, s[6:7]
	s_mov_b32 m0, s95
	v_lshl_add_u64 v[220:221], v[184:185], 0, s[62:63]
	ds_read_b128 v[188:191], v147
	ds_read_b128 v[192:195], v147 offset:1024
	ds_read_b128 v[196:199], v147 offset:2048
	ds_read_b128 v[200:203], v147 offset:3072
	ds_read_b128 v[204:207], v147 offset:4096
	ds_read_b128 v[208:211], v147 offset:5120
	ds_read_b128 v[212:215], v147 offset:6144
	ds_read_b128 v[216:219], v147 offset:7168
	global_load_lds_dwordx4 v[220:221], off
	v_lshl_add_u64 v[184:185], v[184:185], 0, s[64:65]
	s_mov_b32 m0, s96
	s_nop 0
	global_load_lds_dwordx4 v[184:185], off
	s_waitcnt vmcnt(8)
	s_waitcnt lgkmcnt(0)
	s_waitcnt lgkmcnt(0)
	v_mfma_f32_16x16x32_bf16 v[118:121], v[152:155], v[188:191], v[118:121]
	v_mfma_f32_16x16x32_bf16 v[114:117], v[160:163], v[188:191], v[114:117]
	s_barrier
	s_setprio 1
	v_mfma_f32_16x16x32_bf16 v[102:105], v[152:155], v[196:199], v[102:105]
	v_mfma_f32_16x16x32_bf16 v[98:101], v[160:163], v[196:199], v[98:101]
	v_mfma_f32_16x16x32_bf16 v[86:89], v[152:155], v[204:207], v[86:89]
	v_mfma_f32_16x16x32_bf16 v[82:85], v[160:163], v[204:207], v[82:85]
	v_mfma_f32_16x16x32_bf16 v[70:73], v[152:155], v[212:215], v[70:73]
	v_mfma_f32_16x16x32_bf16 v[62:65], v[160:163], v[212:215], v[62:65]
	v_mfma_f32_16x16x32_bf16 v[118:121], v[156:159], v[192:195], v[118:121]
	v_mfma_f32_16x16x32_bf16 v[114:117], v[164:167], v[192:195], v[114:117]
	v_mfma_f32_16x16x32_bf16 v[102:105], v[156:159], v[200:203], v[102:105]
	v_mfma_f32_16x16x32_bf16 v[98:101], v[164:167], v[200:203], v[98:101]
	v_mfma_f32_16x16x32_bf16 v[86:89], v[156:159], v[208:211], v[86:89]
	v_mfma_f32_16x16x32_bf16 v[82:85], v[164:167], v[208:211], v[82:85]
	v_mfma_f32_16x16x32_bf16 v[70:73], v[156:159], v[216:219], v[70:73]
	v_mfma_f32_16x16x32_bf16 v[62:65], v[164:167], v[216:219], v[62:65]
	s_setprio 0
	s_setprio 1
	v_mfma_f32_16x16x32_bf16 v[126:129], v[168:171], v[188:191], v[126:129]
	v_mfma_f32_16x16x32_bf16 v[122:125], v[176:179], v[188:191], v[122:125]
	v_mfma_f32_16x16x32_bf16 v[110:113], v[168:171], v[196:199], v[110:113]
	v_mfma_f32_16x16x32_bf16 v[106:109], v[176:179], v[196:199], v[106:109]
	v_mfma_f32_16x16x32_bf16 v[94:97], v[168:171], v[204:207], v[94:97]
	v_mfma_f32_16x16x32_bf16 v[90:93], v[176:179], v[204:207], v[90:93]
	v_mfma_f32_16x16x32_bf16 v[78:81], v[168:171], v[212:215], v[78:81]
	v_mfma_f32_16x16x32_bf16 v[74:77], v[176:179], v[212:215], v[74:77]
	v_mfma_f32_16x16x32_bf16 v[126:129], v[172:175], v[192:195], v[126:129]
	v_mfma_f32_16x16x32_bf16 v[122:125], v[180:183], v[192:195], v[122:125]
	v_mfma_f32_16x16x32_bf16 v[110:113], v[172:175], v[200:203], v[110:113]
	v_mfma_f32_16x16x32_bf16 v[106:109], v[180:183], v[200:203], v[106:109]
	v_mfma_f32_16x16x32_bf16 v[94:97], v[172:175], v[208:211], v[94:97]
	v_mfma_f32_16x16x32_bf16 v[90:93], v[180:183], v[208:211], v[90:93]
	v_mfma_f32_16x16x32_bf16 v[78:81], v[172:175], v[216:219], v[78:81]
	v_mfma_f32_16x16x32_bf16 v[74:77], v[180:183], v[216:219], v[74:77]
	s_setprio 0
	s_barrier
	s_mov_b32 m0, s97
	v_lshl_add_u64 v[184:185], s[20:21], 0, v[132:133]
	ds_read_b128 v[188:191], v147 offset:16384
	ds_read_b128 v[192:195], v147 offset:17408
	ds_read_b128 v[196:199], v147 offset:18432
	ds_read_b128 v[200:203], v147 offset:19456
	ds_read_b128 v[204:207], v147 offset:20480
	ds_read_b128 v[208:211], v147 offset:21504
	ds_read_b128 v[212:215], v147 offset:22528
	ds_read_b128 v[216:219], v147 offset:23552
	global_load_lds_dwordx4 v[184:185], off
	v_lshl_add_u64 v[220:221], v[184:185], 0, s[16:17]
	s_mov_b32 m0, vcc_lo
	s_nop 0
	global_load_lds_dwordx4 v[220:221], off
	v_lshl_add_u64 v[220:221], v[184:185], 0, s[24:25]
	s_mov_b32 m0, s33
	s_nop 0
	global_load_lds_dwordx4 v[220:221], off
	v_lshl_add_u64 v[220:221], v[184:185], 0, s[26:27]
	s_mov_b32 m0, vcc_hi
	s_nop 0
	global_load_lds_dwordx4 v[220:221], off
	v_lshl_add_u64 v[220:221], s[18:19], 0, v[130:131]
	s_mov_b32 m0, s11
	v_lshl_add_u64 v[222:223], v[220:221], 0, s[16:17]
	global_load_lds_dwordx4 v[220:221], off
	s_mov_b32 m0, s77
	s_nop 0
	global_load_lds_dwordx4 v[222:223], off
	s_waitcnt vmcnt(8)
	s_waitcnt lgkmcnt(0)
	s_waitcnt lgkmcnt(0)
	v_mfma_f32_16x16x32_bf16 v[54:57], v[152:155], v[188:191], v[54:57]
	v_mfma_f32_16x16x32_bf16 v[50:53], v[160:163], v[188:191], v[50:53]
	s_barrier
	s_setprio 1
	v_mfma_f32_16x16x32_bf16 v[38:41], v[152:155], v[196:199], v[38:41]
	v_mfma_f32_16x16x32_bf16 v[34:37], v[160:163], v[196:199], v[34:37]
	v_mfma_f32_16x16x32_bf16 v[22:25], v[152:155], v[204:207], v[22:25]
	v_mfma_f32_16x16x32_bf16 v[18:21], v[160:163], v[204:207], v[18:21]
	v_mfma_f32_16x16x32_bf16 v[6:9], v[152:155], v[212:215], v[6:9]
	v_mfma_f32_16x16x32_bf16 v[2:5], v[160:163], v[212:215], v[2:5]
	v_mfma_f32_16x16x32_bf16 v[54:57], v[156:159], v[192:195], v[54:57]
	v_mfma_f32_16x16x32_bf16 v[50:53], v[164:167], v[192:195], v[50:53]
	v_mfma_f32_16x16x32_bf16 v[38:41], v[156:159], v[200:203], v[38:41]
	v_mfma_f32_16x16x32_bf16 v[34:37], v[164:167], v[200:203], v[34:37]
	v_mfma_f32_16x16x32_bf16 v[22:25], v[156:159], v[208:211], v[22:25]
	v_mfma_f32_16x16x32_bf16 v[18:21], v[164:167], v[208:211], v[18:21]
	v_mfma_f32_16x16x32_bf16 v[6:9], v[156:159], v[216:219], v[6:9]
	v_mfma_f32_16x16x32_bf16 v[2:5], v[164:167], v[216:219], v[2:5]
	s_setprio 0
	s_setprio 1
	v_mfma_f32_16x16x32_bf16 v[66:69], v[168:171], v[188:191], v[66:69]
	v_mfma_f32_16x16x32_bf16 v[58:61], v[176:179], v[188:191], v[58:61]
	v_mfma_f32_16x16x32_bf16 v[46:49], v[168:171], v[196:199], v[46:49]
	v_mfma_f32_16x16x32_bf16 v[42:45], v[176:179], v[196:199], v[42:45]
	v_mfma_f32_16x16x32_bf16 v[30:33], v[168:171], v[204:207], v[30:33]
	v_mfma_f32_16x16x32_bf16 v[26:29], v[176:179], v[204:207], v[26:29]
	v_mfma_f32_16x16x32_bf16 v[14:17], v[168:171], v[212:215], v[14:17]
	v_mfma_f32_16x16x32_bf16 v[10:13], v[176:179], v[212:215], v[10:13]
	v_mfma_f32_16x16x32_bf16 v[66:69], v[172:175], v[192:195], v[66:69]
	v_mfma_f32_16x16x32_bf16 v[58:61], v[180:183], v[192:195], v[58:61]
	v_mfma_f32_16x16x32_bf16 v[46:49], v[172:175], v[200:203], v[46:49]
	v_mfma_f32_16x16x32_bf16 v[42:45], v[180:183], v[200:203], v[42:45]
	v_mfma_f32_16x16x32_bf16 v[30:33], v[172:175], v[208:211], v[30:33]
	v_mfma_f32_16x16x32_bf16 v[26:29], v[180:183], v[208:211], v[26:29]
	v_mfma_f32_16x16x32_bf16 v[14:17], v[172:175], v[216:219], v[14:17]
	v_mfma_f32_16x16x32_bf16 v[10:13], v[180:183], v[216:219], v[10:13]
	s_setprio 0
	s_barrier
	ds_read_b128 v[152:155], v149
	ds_read_b128 v[156:159], v149 offset:1024
	ds_read_b128 v[160:163], v149 offset:2048
	ds_read_b128 v[164:167], v149 offset:3072
	ds_read_b128 v[168:171], v150
	ds_read_b128 v[172:175], v150 offset:1024
	ds_read_b128 v[176:179], v150 offset:2048
	ds_read_b128 v[180:183], v150 offset:3072
	s_mov_b32 m0, s80
	v_lshl_add_u64 v[222:223], v[220:221], 0, s[24:25]
	ds_read_b128 v[188:191], v147 offset:32768
	ds_read_b128 v[192:195], v147 offset:33792
	ds_read_b128 v[196:199], v147 offset:34816
	ds_read_b128 v[200:203], v147 offset:35840
	ds_read_b128 v[204:207], v147 offset:36864
	ds_read_b128 v[208:211], v147 offset:37888
	ds_read_b128 v[212:215], v147 offset:38912
	ds_read_b128 v[216:219], v147 offset:39936
	global_load_lds_dwordx4 v[222:223], off
	v_lshl_add_u64 v[222:223], v[220:221], 0, s[26:27]
	s_mov_b32 m0, s81
	s_nop 0
	global_load_lds_dwordx4 v[222:223], off
	s_waitcnt vmcnt(8)
	s_waitcnt lgkmcnt(0)
	s_waitcnt lgkmcnt(0)
	v_mfma_f32_16x16x32_bf16 v[118:121], v[152:155], v[188:191], v[118:121]
	v_mfma_f32_16x16x32_bf16 v[114:117], v[160:163], v[188:191], v[114:117]
	s_barrier
	s_setprio 1
	v_mfma_f32_16x16x32_bf16 v[102:105], v[152:155], v[196:199], v[102:105]
	v_mfma_f32_16x16x32_bf16 v[98:101], v[160:163], v[196:199], v[98:101]
	v_mfma_f32_16x16x32_bf16 v[86:89], v[152:155], v[204:207], v[86:89]
	v_mfma_f32_16x16x32_bf16 v[82:85], v[160:163], v[204:207], v[82:85]
	v_mfma_f32_16x16x32_bf16 v[70:73], v[152:155], v[212:215], v[70:73]
	v_mfma_f32_16x16x32_bf16 v[62:65], v[160:163], v[212:215], v[62:65]
	v_mfma_f32_16x16x32_bf16 v[118:121], v[156:159], v[192:195], v[118:121]
	v_mfma_f32_16x16x32_bf16 v[114:117], v[164:167], v[192:195], v[114:117]
	v_mfma_f32_16x16x32_bf16 v[102:105], v[156:159], v[200:203], v[102:105]
	v_mfma_f32_16x16x32_bf16 v[98:101], v[164:167], v[200:203], v[98:101]
	v_mfma_f32_16x16x32_bf16 v[86:89], v[156:159], v[208:211], v[86:89]
	v_mfma_f32_16x16x32_bf16 v[82:85], v[164:167], v[208:211], v[82:85]
	v_mfma_f32_16x16x32_bf16 v[70:73], v[156:159], v[216:219], v[70:73]
	v_mfma_f32_16x16x32_bf16 v[62:65], v[164:167], v[216:219], v[62:65]
	s_setprio 0
	s_setprio 1
	v_mfma_f32_16x16x32_bf16 v[126:129], v[168:171], v[188:191], v[126:129]
	v_mfma_f32_16x16x32_bf16 v[122:125], v[176:179], v[188:191], v[122:125]
	v_mfma_f32_16x16x32_bf16 v[110:113], v[168:171], v[196:199], v[110:113]
	v_mfma_f32_16x16x32_bf16 v[106:109], v[176:179], v[196:199], v[106:109]
	v_mfma_f32_16x16x32_bf16 v[94:97], v[168:171], v[204:207], v[94:97]
	v_mfma_f32_16x16x32_bf16 v[90:93], v[176:179], v[204:207], v[90:93]
	v_mfma_f32_16x16x32_bf16 v[78:81], v[168:171], v[212:215], v[78:81]
	v_mfma_f32_16x16x32_bf16 v[74:77], v[176:179], v[212:215], v[74:77]
	v_mfma_f32_16x16x32_bf16 v[126:129], v[172:175], v[192:195], v[126:129]
	v_mfma_f32_16x16x32_bf16 v[122:125], v[180:183], v[192:195], v[122:125]
	v_mfma_f32_16x16x32_bf16 v[110:113], v[172:175], v[200:203], v[110:113]
	v_mfma_f32_16x16x32_bf16 v[106:109], v[180:183], v[200:203], v[106:109]
	v_mfma_f32_16x16x32_bf16 v[94:97], v[172:175], v[208:211], v[94:97]
	v_mfma_f32_16x16x32_bf16 v[90:93], v[180:183], v[208:211], v[90:93]
	v_mfma_f32_16x16x32_bf16 v[78:81], v[172:175], v[216:219], v[78:81]
	v_mfma_f32_16x16x32_bf16 v[74:77], v[180:183], v[216:219], v[74:77]
	s_setprio 0
	s_barrier
	s_mov_b32 m0, s12
	v_lshl_add_u64 v[222:223], v[184:185], 0, s[30:31]
	ds_read_b128 v[188:191], v147 offset:49152
	ds_read_b128 v[192:195], v147 offset:50176
	ds_read_b128 v[196:199], v147 offset:51200
	ds_read_b128 v[200:203], v147 offset:52224
	ds_read_b128 v[204:207], v147 offset:53248
	ds_read_b128 v[208:211], v147 offset:54272
	ds_read_b128 v[212:215], v147 offset:55296
	ds_read_b128 v[216:219], v147 offset:56320
	global_load_lds_dwordx4 v[222:223], off
	v_lshl_add_u64 v[222:223], v[184:185], 0, s[34:35]
	s_mov_b32 m0, s13
	s_nop 0
	global_load_lds_dwordx4 v[222:223], off
	v_lshl_add_u64 v[222:223], v[184:185], 0, s[38:39]
	s_mov_b32 m0, s3
	v_lshl_add_u64 v[184:185], v[184:185], 0, s[40:41]
	global_load_lds_dwordx4 v[222:223], off
	s_mov_b32 m0, s36
	s_nop 0
	global_load_lds_dwordx4 v[184:185], off
	v_lshl_add_u64 v[184:185], v[220:221], 0, s[30:31]
	s_mov_b32 m0, s86
	s_nop 0
	global_load_lds_dwordx4 v[184:185], off
	v_lshl_add_u64 v[184:185], v[220:221], 0, s[34:35]
	s_mov_b32 m0, s87
	s_nop 0
	global_load_lds_dwordx4 v[184:185], off
	s_waitcnt vmcnt(8)
	s_waitcnt lgkmcnt(0)
	s_waitcnt lgkmcnt(0)
	v_mfma_f32_16x16x32_bf16 v[54:57], v[152:155], v[188:191], v[54:57]
	v_mfma_f32_16x16x32_bf16 v[50:53], v[160:163], v[188:191], v[50:53]
	s_barrier
	s_setprio 1
	v_mfma_f32_16x16x32_bf16 v[38:41], v[152:155], v[196:199], v[38:41]
	v_mfma_f32_16x16x32_bf16 v[34:37], v[160:163], v[196:199], v[34:37]
	v_mfma_f32_16x16x32_bf16 v[22:25], v[152:155], v[204:207], v[22:25]
	v_mfma_f32_16x16x32_bf16 v[18:21], v[160:163], v[204:207], v[18:21]
	v_mfma_f32_16x16x32_bf16 v[6:9], v[152:155], v[212:215], v[6:9]
	v_mfma_f32_16x16x32_bf16 v[2:5], v[160:163], v[212:215], v[2:5]
	v_mfma_f32_16x16x32_bf16 v[54:57], v[156:159], v[192:195], v[54:57]
	v_mfma_f32_16x16x32_bf16 v[50:53], v[164:167], v[192:195], v[50:53]
	v_mfma_f32_16x16x32_bf16 v[38:41], v[156:159], v[200:203], v[38:41]
	v_mfma_f32_16x16x32_bf16 v[34:37], v[164:167], v[200:203], v[34:37]
	v_mfma_f32_16x16x32_bf16 v[22:25], v[156:159], v[208:211], v[22:25]
	v_mfma_f32_16x16x32_bf16 v[18:21], v[164:167], v[208:211], v[18:21]
	v_mfma_f32_16x16x32_bf16 v[6:9], v[156:159], v[216:219], v[6:9]
	v_mfma_f32_16x16x32_bf16 v[2:5], v[164:167], v[216:219], v[2:5]
	s_setprio 0
	s_setprio 1
	v_mfma_f32_16x16x32_bf16 v[66:69], v[168:171], v[188:191], v[66:69]
	v_mfma_f32_16x16x32_bf16 v[58:61], v[176:179], v[188:191], v[58:61]
	v_mfma_f32_16x16x32_bf16 v[46:49], v[168:171], v[196:199], v[46:49]
	v_mfma_f32_16x16x32_bf16 v[42:45], v[176:179], v[196:199], v[42:45]
	v_mfma_f32_16x16x32_bf16 v[30:33], v[168:171], v[204:207], v[30:33]
	v_mfma_f32_16x16x32_bf16 v[26:29], v[176:179], v[204:207], v[26:29]
	v_mfma_f32_16x16x32_bf16 v[14:17], v[168:171], v[212:215], v[14:17]
	v_mfma_f32_16x16x32_bf16 v[10:13], v[176:179], v[212:215], v[10:13]
	v_mfma_f32_16x16x32_bf16 v[66:69], v[172:175], v[192:195], v[66:69]
	v_mfma_f32_16x16x32_bf16 v[58:61], v[180:183], v[192:195], v[58:61]
	v_mfma_f32_16x16x32_bf16 v[46:49], v[172:175], v[200:203], v[46:49]
	v_mfma_f32_16x16x32_bf16 v[42:45], v[180:183], v[200:203], v[42:45]
	v_mfma_f32_16x16x32_bf16 v[30:33], v[172:175], v[208:211], v[30:33]
	v_mfma_f32_16x16x32_bf16 v[26:29], v[180:183], v[208:211], v[26:29]
	v_mfma_f32_16x16x32_bf16 v[14:17], v[172:175], v[216:219], v[14:17]
	v_mfma_f32_16x16x32_bf16 v[10:13], v[180:183], v[216:219], v[10:13]
	s_setprio 0
	s_barrier
	s_add_i32 s37, s37, 2
	s_add_u32 s6, s6, 0x100
	s_addc_u32 s7, s7, 0
	s_cmp_gt_u32 s37, 13
	s_cbranch_scc0 .LBB0_1718
	s_and_b64 vcc, exec, s[44:45]
	s_cbranch_vccz .LBB0_1721
	s_cmp_eq_u64 s[4:5], 0
	s_cbranch_scc1 .LBB0_1721
	s_barrier

.Lwtd_15:
	s_cbranch_vccnz .LBB0_1728
	s_andn2_b64 vcc, exec, s[28:29]
	s_cbranch_vccnz .LBB0_1711
	s_branch .LBB0_1711
